# residrev_zero64
# speedup vs baseline: 1.0091x; 1.0047x over previous
.LBB0_468:
	s_ashr_i32 s37, s36, 31
	s_lshl_b64 s[40:41], s[36:37], 19
	s_add_u32 s40, s82, s40
	s_addc_u32 s41, s83, s41
	s_and_b64 s[42:43], s[10:11], exec
	s_cselect_b32 s5, s41, s9
	s_cselect_b32 s7, s40, s8
	s_ashr_i32 s39, s38, 31
	s_lshl_b64 s[42:43], s[38:39], 19
	s_add_u32 s42, s12, s42
	s_addc_u32 s43, s13, s43
	s_and_b64 s[44:45], s[10:11], exec
	s_cselect_b32 s37, s43, s3
	s_cselect_b32 s39, s42, s2
	s_add_u32 s8, s8, 0x40080
	s_addc_u32 s9, s9, 0
	s_add_u32 s33, s2, 0x100
	s_addc_u32 s61, s3, 0
	s_mov_b32 s62, -2
	v_mov_b64_e32 v[2:3], 0
	v_mov_b64_e32 v[4:5], 0
	v_mov_b64_e32 v[6:7], 0
	v_mov_b64_e32 v[8:9], 0
	v_mov_b64_e32 v[10:11], 0
	v_mov_b64_e32 v[12:13], 0
	v_mov_b64_e32 v[14:15], 0
	v_mov_b64_e32 v[16:17], 0
	v_mov_b64_e32 v[18:19], 0
	v_mov_b64_e32 v[20:21], 0
	v_mov_b64_e32 v[22:23], 0
	v_mov_b64_e32 v[24:25], 0
	v_mov_b64_e32 v[26:27], 0
	v_mov_b64_e32 v[28:29], 0
	v_mov_b64_e32 v[30:31], 0
	v_mov_b64_e32 v[32:33], 0
	v_mov_b64_e32 v[34:35], 0
	v_mov_b64_e32 v[36:37], 0
	v_mov_b64_e32 v[38:39], 0
	v_mov_b64_e32 v[40:41], 0
	v_mov_b64_e32 v[42:43], 0
	v_mov_b64_e32 v[44:45], 0
	v_mov_b64_e32 v[46:47], 0
	v_mov_b64_e32 v[48:49], 0
	v_mov_b64_e32 v[58:59], 0
	v_mov_b64_e32 v[60:61], 0
	v_mov_b64_e32 v[62:63], 0
	v_mov_b64_e32 v[64:65], 0
	v_mov_b64_e32 v[74:75], 0
	v_mov_b64_e32 v[76:77], 0
	v_mov_b64_e32 v[78:79], 0
	v_mov_b64_e32 v[80:81], 0
	v_mov_b64_e32 v[82:83], 0
	v_mov_b64_e32 v[84:85], 0
	v_mov_b64_e32 v[86:87], 0
	v_mov_b64_e32 v[88:89], 0
	v_mov_b64_e32 v[94:95], 0
	v_mov_b64_e32 v[96:97], 0
	v_mov_b64_e32 v[98:99], 0
	v_mov_b64_e32 v[100:101], 0
	v_mov_b64_e32 v[102:103], 0
	v_mov_b64_e32 v[104:105], 0
	v_mov_b64_e32 v[106:107], 0
	v_mov_b64_e32 v[108:109], 0
	v_mov_b64_e32 v[114:115], 0
	v_mov_b64_e32 v[116:117], 0
	v_mov_b64_e32 v[118:119], 0
	v_mov_b64_e32 v[120:121], 0
	v_mov_b64_e32 v[122:123], 0
	v_mov_b64_e32 v[124:125], 0
	v_mov_b64_e32 v[130:131], 0
	v_mov_b64_e32 v[132:133], 0
	v_mov_b64_e32 v[134:135], 0
	v_mov_b64_e32 v[136:137], 0
	v_mov_b64_e32 v[138:139], 0
	v_mov_b64_e32 v[140:141], 0
	v_mov_b64_e32 v[146:147], 0
	v_mov_b64_e32 v[148:149], 0
	v_mov_b64_e32 v[150:151], 0
	v_mov_b64_e32 v[152:153], 0
	v_mov_b64_e32 v[154:155], 0
	v_mov_b64_e32 v[156:157], 0
	v_mov_b64_e32 v[158:159], 0
	v_mov_b64_e32 v[160:161], 0

.LBB0_556:
	s_add_u32 s4, s26, 0x80
	s_addc_u32 s5, s27, 0
	s_add_u32 s26, s2, 0x100
	s_addc_u32 s27, s3, 0
	s_mov_b32 s2, 0
	v_mov_b64_e32 v[2:3], 0
	v_mov_b64_e32 v[4:5], 0
	v_mov_b64_e32 v[6:7], 0
	v_mov_b64_e32 v[8:9], 0
	v_mov_b64_e32 v[10:11], 0
	v_mov_b64_e32 v[12:13], 0
	v_mov_b64_e32 v[14:15], 0
	v_mov_b64_e32 v[16:17], 0
	v_mov_b64_e32 v[18:19], 0
	v_mov_b64_e32 v[20:21], 0
	v_mov_b64_e32 v[22:23], 0
	v_mov_b64_e32 v[24:25], 0
	v_mov_b64_e32 v[26:27], 0
	v_mov_b64_e32 v[28:29], 0
	v_mov_b64_e32 v[30:31], 0
	v_mov_b64_e32 v[32:33], 0
	v_mov_b64_e32 v[34:35], 0
	v_mov_b64_e32 v[36:37], 0
	v_mov_b64_e32 v[38:39], 0
	v_mov_b64_e32 v[40:41], 0
	v_mov_b64_e32 v[42:43], 0
	v_mov_b64_e32 v[44:45], 0
	v_mov_b64_e32 v[46:47], 0
	v_mov_b64_e32 v[48:49], 0
	v_mov_b64_e32 v[50:51], 0
	v_mov_b64_e32 v[52:53], 0
	v_mov_b64_e32 v[54:55], 0
	v_mov_b64_e32 v[56:57], 0
	v_mov_b64_e32 v[74:75], 0
	v_mov_b64_e32 v[76:77], 0
	v_mov_b64_e32 v[78:79], 0
	v_mov_b64_e32 v[80:81], 0
	v_mov_b64_e32 v[82:83], 0
	v_mov_b64_e32 v[84:85], 0
	v_mov_b64_e32 v[86:87], 0
	v_mov_b64_e32 v[88:89], 0
	v_mov_b64_e32 v[90:91], 0
	v_mov_b64_e32 v[92:93], 0
	v_mov_b64_e32 v[94:95], 0
	v_mov_b64_e32 v[96:97], 0
	v_mov_b64_e32 v[98:99], 0
	v_mov_b64_e32 v[100:101], 0
	v_mov_b64_e32 v[102:103], 0
	v_mov_b64_e32 v[104:105], 0
	v_mov_b64_e32 v[106:107], 0
	v_mov_b64_e32 v[108:109], 0
	v_mov_b64_e32 v[110:111], 0
	v_mov_b64_e32 v[112:113], 0
	v_mov_b64_e32 v[114:115], 0
	v_mov_b64_e32 v[116:117], 0
	v_mov_b64_e32 v[118:119], 0
	v_mov_b64_e32 v[120:121], 0
	v_mov_b64_e32 v[122:123], 0
	v_mov_b64_e32 v[124:125], 0
	v_mov_b64_e32 v[126:127], 0
	v_mov_b64_e32 v[128:129], 0
	v_mov_b64_e32 v[130:131], 0
	v_mov_b64_e32 v[132:133], 0
	v_mov_b64_e32 v[134:135], 0
	v_mov_b64_e32 v[136:137], 0
	v_mov_b64_e32 v[142:143], 0
	v_mov_b64_e32 v[144:145], 0
	v_mov_b64_e32 v[146:147], 0
	v_mov_b64_e32 v[148:149], 0

.LBB0_597:
	s_ashr_i32 s9, s8, 31
	s_lshl_b64 s[12:13], s[8:9], 19
	s_add_u32 s12, s82, s12
	s_addc_u32 s13, s83, s13
	s_and_b64 s[14:15], s[0:1], exec
	s_cselect_b32 s9, s13, s17
	s_cselect_b32 s34, s12, s16
	s_ashr_i32 s11, s10, 31
	s_lshl_b64 s[14:15], s[10:11], 19
	s_add_u32 s14, s20, s14
	s_addc_u32 s15, s21, s15
	s_and_b64 s[18:19], s[0:1], exec
	s_cselect_b32 s11, s15, s3
	s_cselect_b32 s35, s14, s2
	s_add_u32 s16, s16, 0x40080
	s_addc_u32 s17, s17, 0
	s_add_u32 s33, s2, 0x100
	s_addc_u32 s36, s3, 0
	s_mov_b32 s37, -2
	v_mov_b64_e32 v[2:3], 0
	v_mov_b64_e32 v[4:5], 0
	v_mov_b64_e32 v[6:7], 0
	v_mov_b64_e32 v[8:9], 0
	v_mov_b64_e32 v[10:11], 0
	v_mov_b64_e32 v[12:13], 0
	v_mov_b64_e32 v[14:15], 0
	v_mov_b64_e32 v[16:17], 0
	v_mov_b64_e32 v[18:19], 0
	v_mov_b64_e32 v[20:21], 0
	v_mov_b64_e32 v[22:23], 0
	v_mov_b64_e32 v[24:25], 0
	v_mov_b64_e32 v[26:27], 0
	v_mov_b64_e32 v[28:29], 0
	v_mov_b64_e32 v[30:31], 0
	v_mov_b64_e32 v[32:33], 0
	v_mov_b64_e32 v[34:35], 0
	v_mov_b64_e32 v[36:37], 0
	v_mov_b64_e32 v[38:39], 0
	v_mov_b64_e32 v[40:41], 0
	v_mov_b64_e32 v[42:43], 0
	v_mov_b64_e32 v[44:45], 0
	v_mov_b64_e32 v[46:47], 0
	v_mov_b64_e32 v[48:49], 0
	v_mov_b64_e32 v[50:51], 0
	v_mov_b64_e32 v[52:53], 0
	v_mov_b64_e32 v[54:55], 0
	v_mov_b64_e32 v[56:57], 0
	v_mov_b64_e32 v[58:59], 0
	v_mov_b64_e32 v[60:61], 0
	v_mov_b64_e32 v[62:63], 0
	v_mov_b64_e32 v[64:65], 0
	v_mov_b64_e32 v[66:67], 0
	v_mov_b64_e32 v[68:69], 0
	v_mov_b64_e32 v[70:71], 0
	v_mov_b64_e32 v[72:73], 0
	v_mov_b64_e32 v[74:75], 0
	v_mov_b64_e32 v[76:77], 0
	v_mov_b64_e32 v[78:79], 0
	v_mov_b64_e32 v[80:81], 0
	v_mov_b64_e32 v[82:83], 0
	v_mov_b64_e32 v[84:85], 0
	v_mov_b64_e32 v[86:87], 0
	v_mov_b64_e32 v[88:89], 0
	v_mov_b64_e32 v[90:91], 0
	v_mov_b64_e32 v[92:93], 0
	v_mov_b64_e32 v[94:95], 0
	v_mov_b64_e32 v[96:97], 0
	v_mov_b64_e32 v[98:99], 0
	v_mov_b64_e32 v[100:101], 0
	v_mov_b64_e32 v[102:103], 0
	v_mov_b64_e32 v[104:105], 0
	v_mov_b64_e32 v[106:107], 0
	v_mov_b64_e32 v[108:109], 0
	v_mov_b64_e32 v[110:111], 0
	v_mov_b64_e32 v[112:113], 0
	v_mov_b64_e32 v[114:115], 0
	v_mov_b64_e32 v[116:117], 0
	v_mov_b64_e32 v[118:119], 0
	v_mov_b64_e32 v[120:121], 0
	v_mov_b64_e32 v[122:123], 0
	v_mov_b64_e32 v[124:125], 0
	v_mov_b64_e32 v[126:127], 0
	v_mov_b64_e32 v[128:129], 0
